# layer-0 SSM tables deferred from phase 0 to the start of the table blocks' in-proj phase (they keep one in-proj tile; 128 other blocks take a fifth tile)
# speedup vs baseline: 1.0049x; 1.0049x over previous
.LBB0_8:
	v_writelane_b32 v255, 0, 61
	v_writelane_b32 v255, 0, 62
	s_add_u32 s0, s0, 0x120
	s_addc_u32 s1, s1, 0
	v_writelane_b32 v253, s0, 4
	v_lshrrev_b32_e32 v1, 20, v0
	v_lshrrev_b32_e32 v0, 10, v0
	v_writelane_b32 v253, s1, 5
	s_and_b32 s0, s52, 7
	v_writelane_b32 v253, s0, 6
	s_lshr_b32 s0, s52, 3
	v_writelane_b32 v253, s0, 7
	s_lshl_b32 s0, s52, 3
	s_cmpk_lt_i32 s52, 0x510
	v_writelane_b32 v253, s0, 8
	s_cselect_b64 s[0:1], -1, 0
	v_writelane_b32 v253, s0, 9
	s_cmp_gt_i32 s52, 31
	v_or_b32_e32 v0, v0, v1
	v_writelane_b32 v253, s1, 10
	s_cselect_b64 s[0:1], -1, 0
	v_writelane_b32 v253, s0, 11
	s_cmpk_lt_u32 s52, 0x510
	s_mov_b32 s54, s52
	v_writelane_b32 v253, s1, 12
	s_cselect_b64 s[0:1], -1, 0
	v_writelane_b32 v253, s0, 13
	s_ashr_i32 s53, s52, 31
	s_lshl_b64 s[6:7], s[52:53], 18
	v_writelane_b32 v253, s1, 14
	s_sub_i32 s0, s52, 32
	v_writelane_b32 v253, s0, 15
	v_writelane_b32 v253, s6, 16
	s_lshl_b32 s0, s52, 6
	v_mbcnt_lo_u32_b32 v2, -1, 0
	v_writelane_b32 v253, s7, 17
	s_lshl_b64 s[6:7], s[52:53], 17
	v_writelane_b32 v253, s6, 18
	s_mov_b32 s53, s0
	s_lshl_b32 s0, s52, 9
	v_writelane_b32 v253, s7, 19
	v_writelane_b32 v253, s0, 20
	s_add_u32 s0, s2, 0x11a48200
	s_addc_u32 s1, s3, 0
	v_writelane_b32 v253, s0, 21
	v_mbcnt_hi_u32_b32 v172, -1, v2
	v_and_b32_e32 v2, 64, v172
	v_writelane_b32 v253, s1, 22
	s_add_u32 s0, s2, 0x11a48400
	s_addc_u32 s1, s3, 0
	v_writelane_b32 v253, s0, 23
	v_mov_b32_e32 v1, 0
	v_mov_b32_e32 v167, 0x358637bd
	v_writelane_b32 v253, s1, 24
	s_add_u32 s0, s2, 0x11a48500
	s_addc_u32 s1, s3, 0
	v_writelane_b32 v253, s0, 25
	v_mov_b32_e32 v168, 0x3c0881c4
	v_mov_b32_e32 v169, 0xbab64f3b
	v_writelane_b32 v253, s1, 26
	s_add_u32 s0, s2, 0x11a48600
	s_addc_u32 s1, s3, 0
	v_writelane_b32 v253, s0, 27
	v_mov_b32_e32 v170, 0x3ca908c9
	v_mov_b32_e32 v171, 1
	v_writelane_b32 v253, s1, 28
	s_add_u32 s0, s2, 0x11a48700
	s_addc_u32 s1, s3, 0
	v_writelane_b32 v253, s0, 29
	v_add_u32_e32 v173, 64, v2
	v_xor_b32_e32 v174, 32, v172
	v_writelane_b32 v253, s1, 30
	s_add_u32 s0, s2, 0x11a48800
	s_addc_u32 s1, s3, 0
	v_writelane_b32 v253, s0, 31
	v_xor_b32_e32 v175, 16, v172
	v_xor_b32_e32 v193, 2, v172
	v_writelane_b32 v253, s1, 32
	s_add_u32 s0, s2, 0x11a48900
	s_addc_u32 s1, s3, 0
	v_writelane_b32 v253, s0, 33
	v_xor_b32_e32 v252, 1, v172
	v_mov_b32_e32 v180, 0xbe48000
	v_writelane_b32 v253, s1, 34
	s_add_u32 s0, s2, 0x11a48a00
	s_addc_u32 s1, s3, 0
	v_writelane_b32 v253, s0, 35
	v_mov_b32_e32 v181, 0xab48000
	v_mov_b32_e32 v182, 0xd848000
	v_writelane_b32 v253, s1, 36
	s_add_u32 s0, s2, 0x11a48b00
	s_addc_u32 s1, s3, 0
	v_writelane_b32 v253, s0, 37
	v_mov_b32_e32 v183, 0xb1c8000
	v_mov_b32_e32 v184, 0x2c00
	v_writelane_b32 v253, s1, 38
	s_add_u32 s0, s2, 0x11a48c00
	s_addc_u32 s1, s3, 0
	v_writelane_b32 v253, s0, 39
	v_mov_b32_e32 v185, 0x20be0
	v_mov_b32_e32 v186, 0x7f800000
	v_writelane_b32 v253, s1, 40
	s_add_u32 s0, s2, 0x11a48d00
	s_addc_u32 s1, s3, 0
	v_writelane_b32 v253, s0, 41
	v_not_b32_e32 v187, 63
	v_not_b32_e32 v188, 31
	v_writelane_b32 v253, s1, 42
	s_add_u32 s0, s2, 0x11a48e00
	s_addc_u32 s1, s3, 0
	v_writelane_b32 v253, s0, 43
	v_mov_b32_e32 v189, 0x7fc00000
	v_mov_b32_e32 v190, 0xffffff00
	v_writelane_b32 v253, s1, 44
	s_add_u32 s0, s2, 0x11a48f00
	s_addc_u32 s1, s3, 0
	v_writelane_b32 v253, s0, 45
	v_mov_b32_e32 v191, 0xfffffe80
	v_mov_b32_e32 v192, 3
	v_writelane_b32 v253, s1, 46
	s_add_u32 s0, s2, 0x11a49000
	s_addc_u32 s1, s3, 0
	v_writelane_b32 v253, s0, 47
	v_mov_b32_e32 v156, 0xf149f2ca
	s_movk_i32 s33, 0x6000
	v_writelane_b32 v253, s1, 48
	s_add_u32 s0, s2, 0x11a49100
	s_addc_u32 s1, s3, 0
	v_writelane_b32 v253, s0, 49
	s_movk_i32 s83, 0x2000
	s_movk_i32 s86, 0x1fff
	v_writelane_b32 v253, s1, 50
	s_add_u32 s0, s2, 0x11a49200
	s_addc_u32 s1, s3, 0
	v_writelane_b32 v253, s0, 51
	s_movk_i32 s77, 0x1000
	s_mov_b32 s70, 0x800000
	v_writelane_b32 v253, s1, 52
	s_add_u32 s0, s2, 0x11a49300
	s_addc_u32 s1, s3, 0
	v_writelane_b32 v253, s0, 53
	s_cmp_eq_u32 s10, 15
	s_movk_i32 s96, 0x5000
	v_writelane_b32 v253, s1, 54
	s_cselect_b64 s[0:1], -1, 0
	v_writelane_b32 v253, s0, 55
	s_cmp_eq_u32 s10, 14
	s_mov_b32 s50, 0x8000
	v_writelane_b32 v253, s1, 56
	s_cselect_b64 s[0:1], -1, 0
	v_writelane_b32 v253, s0, 57
	s_cmp_eq_u32 s10, 13
	s_movk_i32 s55, 0xff
	v_writelane_b32 v253, s1, 58
	s_cselect_b64 s[0:1], -1, 0
	v_writelane_b32 v253, s0, 59
	s_cmp_eq_u32 s10, 12
	s_mov_b32 s51, 0x40000
	v_writelane_b32 v253, s1, 60
	s_cselect_b64 s[0:1], -1, 0
	v_writelane_b32 v253, s0, 61
	s_cmp_eq_u32 s10, 11
	s_movk_i32 s48, 0x1200
	v_writelane_b32 v253, s1, 62
	s_cselect_b64 s[0:1], -1, 0
	v_writelane_b32 v253, s0, 63
	s_cmp_eq_u32 s10, 10
	s_movk_i32 s31, 0x7fff
	v_writelane_b32 v254, s1, 0
	s_cselect_b64 s[0:1], -1, 0
	v_writelane_b32 v254, s0, 1
	s_cmp_eq_u32 s10, 9
	s_movk_i32 s49, 0x3000
	v_writelane_b32 v254, s1, 2
	s_cselect_b64 s[0:1], -1, 0
	v_writelane_b32 v254, s0, 3
	s_cmp_eq_u32 s10, 8
	s_movk_i32 s56, 0x4000
	v_writelane_b32 v254, s1, 4
	s_cselect_b64 s[0:1], -1, 0
	v_writelane_b32 v254, s0, 5
	s_cmp_eq_u32 s10, 7
	s_mov_b32 s57, 0x27fff
	v_writelane_b32 v254, s1, 6
	s_cselect_b64 s[0:1], -1, 0
	v_writelane_b32 v254, s0, 7
	s_cmp_eq_u32 s10, 6
	s_movk_i32 s65, 0x400
	v_writelane_b32 v254, s1, 8
	s_cselect_b64 s[0:1], -1, 0
	v_writelane_b32 v254, s0, 9
	s_cmp_eq_u32 s10, 5
	s_mov_b32 s97, 0x12000
	v_writelane_b32 v254, s1, 10
	s_cselect_b64 s[0:1], -1, 0
	v_writelane_b32 v254, s0, 11
	s_cmp_eq_u32 s10, 4
	s_mov_b32 s87, 0xc000
	v_writelane_b32 v254, s1, 12
	s_cselect_b64 s[0:1], -1, 0
	v_writelane_b32 v254, s0, 13
	s_cmp_eq_u32 s10, 3
	s_movk_i32 s75, 0x404
	v_writelane_b32 v254, s1, 14
	s_cselect_b64 s[0:1], -1, 0
	v_writelane_b32 v254, s0, 15
	s_cmp_eq_u32 s10, 2
	s_mov_b32 s71, 0xc2ce8ed0
	v_writelane_b32 v254, s1, 16
	s_cselect_b64 s[0:1], -1, 0
	v_writelane_b32 v254, s0, 17
	s_cmp_eq_u32 s10, 1
	s_mov_b32 s30, 0x42b17218
	v_writelane_b32 v254, s1, 18
	s_cselect_b64 s[0:1], -1, 0
	v_writelane_b32 v254, s0, 19
	s_cmp_eq_u32 s10, 0
	s_mov_b32 s21, 0x437f0000
	v_writelane_b32 v254, s1, 20
	s_cselect_b64 s[0:1], -1, 0
	v_writelane_b32 v254, s0, 21
	s_mov_b32 s35, 0x3e38aa3b
	s_movk_i32 s58, 0x21ff
	v_writelane_b32 v254, s1, 22
	s_lshl_b32 s0, s10, 8
	s_add_u32 s0, s4, s0
	s_addc_u32 s1, s5, 0
	s_add_u32 s4, s0, 0x1400
	s_addc_u32 s5, s1, 0
	v_writelane_b32 v254, s4, 23
	s_add_u32 s0, s0, 0x2400
	s_addc_u32 s1, s1, 0
	v_writelane_b32 v254, s5, 24
	v_writelane_b32 v254, s0, 25
	s_mov_b32 s29, 0
	s_mov_b64 s[84:85], 0x800
	v_writelane_b32 v254, s1, 26
	s_add_u32 s0, s2, 0x11a4b400
	s_addc_u32 s1, s3, 0
	v_writelane_b32 v254, s0, 27
	s_mov_b64 s[24:25], 0x80
	s_mov_b32 s76, 0x3fb8aa3b
	v_writelane_b32 v254, s1, 28
	s_add_u32 s0, s2, 0x11a4b500
	s_addc_u32 s1, s3, 0
	v_writelane_b32 v254, s0, 29
	s_mov_b64 s[78:79], 0x1ff80
	s_mov_b32 s64, 0x3f803f80
	v_writelane_b32 v254, s1, 30
	s_movk_i32 s0, 0x3ff
	v_and_or_b32 v0, v0, s0, v166
	s_add_i32 s0, 0, 0x4400
	v_writelane_b32 v254, s0, 31
	s_add_i32 s0, 0, 0x6400
	v_writelane_b32 v254, s0, 32
	s_add_i32 s0, 0, 0xa400
	v_writelane_b32 v254, s0, 33
	s_add_i32 s0, 0, 0x11800
	v_writelane_b32 v254, s0, 34
	s_add_i32 s0, 0, 0x11000
	v_writelane_b32 v254, s0, 35
	s_add_i32 s0, 0, 0x21140
	v_writelane_b32 v254, s0, 36
	s_add_i32 s0, 0, 0x21144
	v_writelane_b32 v254, s0, 37
	v_readlane_b32 s0, v253, 2
	v_readlane_b32 s1, v253, 3
	s_nop 0
	v_writelane_b32 v254, s0, 38
	v_cmp_eq_u32_e64 s[0:1], 0, v0
	s_nop 1
	v_writelane_b32 v254, s0, 39
	s_nop 1
	v_writelane_b32 v254, s1, 40
	v_writelane_b32 v254, s53, 41
	v_writelane_b32 v254, s52, 42
	s_nop 1
	v_writelane_b32 v254, s53, 43
	v_writelane_b32 v254, s54, 44
	s_branch .LBB0_13

.LBB0_1293:
	s_andn2_b64 vcc, exec, s[0:1]
	s_cbranch_vccnz .LBB0_1681
	v_readlane_b32 s0, v255, 42
	s_cmp_eq_u32 s0, 0
	s_cbranch_scc0 .LBB0_1681
	v_readlane_b32 s0, v255, 22
	s_cmpk_gt_i32 s0, 0x41f
	v_readlane_b32 s1, v255, 23
	s_cbranch_scc1 .LBB0_1681
	s_add_u32 s0, s72, 0xd048000
	s_addc_u32 s1, s73, 0
	v_writelane_b32 v255, s0, 44
	s_add_u32 s52, s72, 0xafc8000
	s_addc_u32 s53, s73, 0
	v_writelane_b32 v255, s1, 45
	s_add_u32 s54, s72, 0xb1c8000
	v_readlane_b32 s0, v255, 28
	s_addc_u32 s55, s73, 0
	s_lshl_b32 s28, s0, 7
	v_readlane_b32 s1, v255, 29
	s_add_u32 s56, s72, 0x80000
	s_addc_u32 s57, s73, 0
	v_readlane_b32 s0, v255, 20
	v_readlane_b32 s1, v255, 21
	s_add_u32 s2, s0, 0x9000000
	s_addc_u32 s3, s1, 0
	s_add_u32 s66, s0, 0x7000000
	s_addc_u32 s67, s1, 0
	s_add_u32 s90, s0, 0x6800000
	v_writelane_b32 v255, s2, 42
	s_addc_u32 s91, s1, 0
	s_add_u32 s18, s0, 0x6000000
	v_writelane_b32 v255, s3, 43
	s_addc_u32 s19, s1, 0
	v_readlane_b32 s0, v255, 22
	s_mov_b32 s20, s0
	s_lshl_b32 s62, s0, 8
	s_lshl_b32 s63, s89, 8
	v_readlane_b32 s1, v255, 23
	s_mov_b32 s32, 0
	s_branch .LBB0_1299

.LBB0_1298:
	s_or_b64 exec, exec, s[0:1]
	s_add_i32 s20, s12, s89
	s_add_i32 s62, s62, s63
	s_cmpk_lg_i32 s89, 0x100
	s_cbranch_scc1 .Lip_keep
	s_cmp_eq_u32 s32, 1
	s_cbranch_scc0 .Lip_a
	s_mov_b32 s32, 0
	s_branch .LBB0_1680
.Lip_a:
	v_readlane_b32 s0, v255, 22
	s_and_b32 s1, s0, 31
	s_cmpk_lt_i32 s1, 4
	s_cbranch_scc1 .LBB0_1680
	s_cmpk_lt_i32 s20, 0x400
	s_cbranch_scc1 .Lip_keep
	s_cmpk_lt_i32 s1, 20
	s_cbranch_scc0 .LBB0_1680
	s_lshr_b32 s0, s0, 5
	s_lshl_b32 s0, s0, 4
	s_add_i32 s0, s0, s1
	s_sub_i32 s0, s0, 4
	s_mov_b32 s32, 1
	s_cmpk_lt_i32 s0, 96
	s_cbranch_scc1 .Lip_tb
	s_add_i32 s20, s0, 0x3a0
	s_branch .Lip_set
.Lip_tb:
	s_mul_hi_u32 s1, s0, 0xaaaaaaab
	s_lshr_b32 s1, s1, 1
	s_mul_i32 s20, s1, 3
	s_sub_i32 s0, s0, s20
	s_add_i32 s0, s0, 1
	s_lshl_b32 s0, s0, 8
	s_lshr_b32 s20, s1, 2
	s_lshl_b32 s20, s20, 5
	s_and_b32 s1, s1, 3
	s_add_i32 s20, s20, s1
	s_add_i32 s20, s20, s0
.Lip_set:
	s_lshl_b32 s62, s20, 8

.LBB0_1830:
	s_cmpk_lg_i32 s89, 0x100
	s_cbranch_scc1 .Ldt_a
	v_readlane_b32 s2, v255, 61
	s_cmp_lg_u32 s2, 0
	s_cbranch_scc1 .Ldt_a
	s_mov_b64 s[0:1], 0

.Let_done:
	s_cmpk_lg_i32 s89, 0x100
	s_cbranch_scc1 .Ldt_done
	v_readlane_b32 s3, v255, 22
	s_and_b32 s3, s3, 31
	s_cmpk_lt_i32 s3, 4
	s_cbranch_scc0 .Ldt_done
	v_readlane_b32 s3, v255, 61
	s_cmp_eq_u32 s2, 1
	s_cbranch_scc0 .Ldt_n1
	s_cmp_eq_u32 s3, 0
	s_cbranch_scc0 .Ldt_done
	s_mov_b32 s3, 1
	s_nop 0
	v_writelane_b32 v255, s3, 61
	s_mov_b32 s16, 0
	s_branch .Ldt_done
.Ldt_n1:
	s_cmp_eq_u32 s2, 0
	s_cbranch_scc0 .Ldt_done
	s_cmp_eq_u32 s3, 1
	s_cbranch_scc0 .Ldt_done
	s_mov_b32 s3, 2
	s_nop 0
	v_writelane_b32 v255, s3, 61
	s_mov_b32 s16, 2
	s_mov_b64 s[0:1], 0
	s_waitcnt vmcnt(0) lgkmcnt(0)
	s_barrier
	s_branch .LBB0_1969
